# group / XCD barrier poll loop without the s_sleep between polls
# baseline (speedup 1.0000x reference)
.Lgb_poll:
	global_load_dword v0, v99, s[8:9] sc1
	s_add_u32 s4, s4, 1
	s_waitcnt vmcnt(0)
	v_readfirstlane_b32 s1, v0
	s_nop 3
	s_cmp_ge_u32 s1, s2
	s_cbranch_scc1 .Lgb_done
	s_cmp_gt_u32 s4, 0x100000
	s_cbranch_scc1 .Lgb_done
	s_branch .Lgb_poll
